# gate/up epilogue: output rows transposed through a per-wave LDS scratch so each 16-byte store instruction covers 16 rows x 64 contiguous bytes with adjacent lanes contiguous (coalesced) instead of 64
# baseline (speedup 1.0000x reference)
.LBB0_607:
	v_readlane_b32 s6, v253, 4
	v_readlane_b32 s7, v253, 5
	v_lshrrev_b32_e32 v135, 1, v146
	s_load_dwordx2 s[22:23], s[6:7], 0x98
	v_and_b32_e32 v136, 1, v146
	v_lshl_add_u32 v134, s5, 8, v135
	v_lshlrev_b32_e32 v134, 7, v134
	v_lshl_or_b32 v134, v136, 6, v134
	v_and_b32_e32 v212, 63, v146
	v_lshrrev_b32_e32 v213, 6, v146
	v_mul_u32_u24_e32 v213, 0x500, v213
	v_add_u32_e32 v213, 0x20800, v213
	v_and_b32_e32 v214, 15, v212
	v_mul_u32_u24_e32 v214, 0x50, v214
	v_lshrrev_b32_e32 v218, 4, v212
	v_lshl_add_u32 v214, v218, 4, v214
	v_add_u32_e32 v214, v213, v214
	v_lshrrev_b32_e32 v216, 2, v212
	v_mul_u32_u24_e32 v215, 0x50, v216
	v_and_b32_e32 v217, 3, v212
	v_lshl_add_u32 v215, v217, 4, v215
	v_add_u32_e32 v215, v213, v215
	v_and_b32_e32 v218, 0xffffffc0, v149
	v_or_b32_e32 v216, v218, v216
	v_and_b32_e32 v218, 0xffffffe0, v177
	v_lshl_or_b32 v217, v217, 3, v218
	v_lshl_add_u32 v162, s5, 8, v216
	v_lshl_or_b32 v164, s4, 7, v217
	s_waitcnt lgkmcnt(0)
	s_add_u32 s4, s22, 0x1a700000
	s_addc_u32 s5, s23, 0
	global_load_dwordx4 v[236:239], v134, s[4:5]
	global_load_dwordx4 v[240:243], v134, s[4:5] offset:16
	global_load_dwordx4 v[244:247], v134, s[4:5] offset:32
	global_load_dwordx4 v[194:197], v134, s[4:5] offset:48
	s_mov_b32 s18, 0xf800000
	v_ashrrev_i32_e32 v165, 31, v164
	v_or_b32_e32 v168, 16, v162
	v_or_b32_e32 v166, 32, v162
	v_or_b32_e32 v170, 48, v162
	v_add_u32_e32 v172, 0x80, v162
	v_add_u32_e32 v184, 0x90, v162
	v_add_u32_e32 v188, 0xa0, v162
	v_add_u32_e32 v192, 0xb0, v162
	v_lshl_add_u64 v[132:133], v[164:165], 1, s[22:23]
	v_lshlrev_b32_e32 v135, 2, v135
	v_add_u32_e32 v135, 0x20240, v135
	s_waitcnt vmcnt(0)
	v_pk_add_f32 v[238:239], v[238:239], v[242:243]
	v_pk_add_f32 v[236:237], v[236:237], v[240:241]
	v_pk_add_f32 v[246:247], v[246:247], v[196:197]
	v_pk_add_f32 v[244:245], v[244:245], v[194:195]
	s_mov_b64 s[4:5], 0x12f00000
	v_add_f32_e32 v236, v236, v237
	v_add_f32_e32 v238, v238, v239
	v_add_f32_e32 v244, v244, v245
	v_add_f32_e32 v246, v246, v247
	v_add_f32_e32 v236, v236, v238
	v_add_f32_e32 v244, v244, v246
	v_lshl_add_u64 v[132:133], v[132:133], 0, s[4:5]
	v_add_f32_e32 v236, v236, v244
	s_nop 1
	v_mov_b32_dpp v237, v236 quad_perm:[1,0,3,2] row_mask:0xf bank_mask:0xf
	s_nop 0
	v_add_f32_e32 v236, v236, v237
	v_fmamk_f32 v137, v236, 0x3a000000, v204
	v_cmp_gt_f32_e32 vcc, s18, v137
	v_mul_f32_e32 v154, 0x4f800000, v137
	s_nop 0
	v_cndmask_b32_e32 v137, v137, v154, vcc
	v_sqrt_f32_e32 v154, v137
	s_nop 0
	v_add_u32_e32 v155, -1, v154
	v_fma_f32 v156, -v155, v154, v137
	v_cmp_ge_f32_e64 s[6:7], 0, v156
	v_add_u32_e32 v156, 1, v154
	s_nop 0
	v_cndmask_b32_e64 v155, v154, v155, s[6:7]
	v_fma_f32 v154, -v156, v154, v137
	v_cmp_lt_f32_e64 s[6:7], 0, v154
	s_nop 1
	v_cndmask_b32_e64 v154, v155, v156, s[6:7]
	v_mul_f32_e32 v155, 0x37800000, v154
	v_cndmask_b32_e32 v154, v154, v155, vcc
	v_cmp_class_f32_e32 vcc, v137, v205
	s_nop 1
	v_cndmask_b32_e32 v137, v154, v137, vcc
	v_div_scale_f32 v154, s[4:5], v137, v137, 1.0
	v_rcp_f32_e32 v155, v154
	s_nop 0
	v_fma_f32 v156, -v154, v155, 1.0
	v_fmac_f32_e32 v155, v156, v155
	v_div_scale_f32 v156, vcc, 1.0, v137, 1.0
	v_mul_f32_e32 v157, v156, v155
	v_fma_f32 v198, -v154, v157, v156
	v_fmac_f32_e32 v157, v198, v155
	v_fma_f32 v154, -v154, v157, v156
	v_div_fmas_f32 v154, v154, v155, v157
	v_div_fixup_f32 v199, v154, v137, 1.0
	ds_write_b32 v135, v199
	v_lshlrev_b32_e32 v134, 2, v149
	v_add_u32_e32 v134, 0x20240, v134
	s_waitcnt lgkmcnt(0)
	s_barrier
	ds_read_b32 v180, v134
	ds_read_b32 v176, v134 offset:64
	ds_read_b32 v174, v134 offset:128
	ds_read_b32 v178, v134 offset:192
	ds_read_b32 v182, v134 offset:512
	ds_read_b32 v186, v134 offset:576
	ds_read_b32 v190, v134 offset:640
	ds_read_b32 v130, v134 offset:704
	s_movk_i32 s6, 0x2c00
	s_waitcnt lgkmcnt(0)
	v_pk_mul_f32 v[126:127], v[126:127], v[180:181] op_sel_hi:[1,0]
	v_pk_mul_f32 v[118:119], v[118:119], v[180:181] op_sel_hi:[1,0]
	v_pk_mul_f32 v[128:129], v[128:129], v[180:181] op_sel_hi:[1,0]
	v_pk_mul_f32 v[120:121], v[120:121], v[180:181] op_sel_hi:[1,0]
	v_pk_mul_f32 v[122:123], v[122:123], v[180:181] op_sel_hi:[1,0]
	v_pk_mul_f32 v[124:125], v[124:125], v[180:181] op_sel_hi:[1,0]
	v_pk_mul_f32 v[110:111], v[110:111], v[176:177] op_sel_hi:[1,0]
	v_pk_mul_f32 v[102:103], v[102:103], v[176:177] op_sel_hi:[1,0]
	v_pk_mul_f32 v[112:113], v[112:113], v[176:177] op_sel_hi:[1,0]
	v_pk_mul_f32 v[104:105], v[104:105], v[176:177] op_sel_hi:[1,0]
	v_pk_mul_f32 v[106:107], v[106:107], v[176:177] op_sel_hi:[1,0]
	v_pk_mul_f32 v[108:109], v[108:109], v[176:177] op_sel_hi:[1,0]
	v_pk_mul_f32 v[94:95], v[94:95], v[174:175] op_sel_hi:[1,0]
	v_pk_mul_f32 v[86:87], v[86:87], v[174:175] op_sel_hi:[1,0]
	v_pk_mul_f32 v[96:97], v[96:97], v[174:175] op_sel_hi:[1,0]
	v_pk_mul_f32 v[88:89], v[88:89], v[174:175] op_sel_hi:[1,0]
	v_pk_mul_f32 v[90:91], v[90:91], v[174:175] op_sel_hi:[1,0]
	v_pk_mul_f32 v[92:93], v[92:93], v[174:175] op_sel_hi:[1,0]
	v_pk_mul_f32 v[78:79], v[78:79], v[178:179] op_sel_hi:[1,0]
	v_pk_mul_f32 v[70:71], v[70:71], v[178:179] op_sel_hi:[1,0]
	v_pk_mul_f32 v[80:81], v[80:81], v[178:179] op_sel_hi:[1,0]
	v_pk_mul_f32 v[72:73], v[72:73], v[178:179] op_sel_hi:[1,0]
	v_pk_mul_f32 v[74:75], v[74:75], v[178:179] op_sel_hi:[1,0]
	v_pk_mul_f32 v[76:77], v[76:77], v[178:179] op_sel_hi:[1,0]
	v_pk_mul_f32 v[62:63], v[62:63], v[182:183] op_sel_hi:[1,0]
	v_pk_mul_f32 v[54:55], v[54:55], v[182:183] op_sel_hi:[1,0]
	v_pk_mul_f32 v[64:65], v[64:65], v[182:183] op_sel_hi:[1,0]
	v_pk_mul_f32 v[56:57], v[56:57], v[182:183] op_sel_hi:[1,0]
	v_pk_mul_f32 v[58:59], v[58:59], v[182:183] op_sel_hi:[1,0]
	v_pk_mul_f32 v[60:61], v[60:61], v[182:183] op_sel_hi:[1,0]
	v_pk_mul_f32 v[46:47], v[46:47], v[186:187] op_sel_hi:[1,0]
	v_pk_mul_f32 v[38:39], v[38:39], v[186:187] op_sel_hi:[1,0]
	v_pk_mul_f32 v[48:49], v[48:49], v[186:187] op_sel_hi:[1,0]
	v_pk_mul_f32 v[40:41], v[40:41], v[186:187] op_sel_hi:[1,0]
	v_pk_mul_f32 v[42:43], v[42:43], v[186:187] op_sel_hi:[1,0]
	v_pk_mul_f32 v[44:45], v[44:45], v[186:187] op_sel_hi:[1,0]
	v_pk_mul_f32 v[30:31], v[30:31], v[190:191] op_sel_hi:[1,0]
	v_pk_mul_f32 v[22:23], v[22:23], v[190:191] op_sel_hi:[1,0]
	v_pk_mul_f32 v[32:33], v[32:33], v[190:191] op_sel_hi:[1,0]
	v_pk_mul_f32 v[24:25], v[24:25], v[190:191] op_sel_hi:[1,0]
	v_pk_mul_f32 v[26:27], v[26:27], v[190:191] op_sel_hi:[1,0]
	v_pk_mul_f32 v[28:29], v[28:29], v[190:191] op_sel_hi:[1,0]
	v_pk_mul_f32 v[136:137], v[116:117], v[180:181] op_sel_hi:[1,0]
	v_pk_mul_f32 v[116:117], v[114:115], v[180:181] op_sel_hi:[1,0]
	v_mul_f32_e32 v114, 0xbfb8aa3b, v126
	v_mul_f32_e32 v115, 0xbfb8aa3b, v127
	v_exp_f32_e32 v114, v114
	v_exp_f32_e32 v115, v115
	v_mad_i64_i32 v[134:135], s[4:5], v162, s6, v[132:133]
	v_add_f32_e32 v114, 1.0, v114
	v_add_f32_e32 v115, 1.0, v115
	v_rcp_f32_e32 v114, v114
	v_rcp_f32_e32 v115, v115
	s_nop 0
	v_pk_mul_f32 v[114:115], v[126:127], v[114:115]
	s_nop 0
	v_pk_mul_f32 v[114:115], v[118:119], v[114:115]
	s_nop 0
	v_cvt_pk_bf16_f32 v114, v114, v115
	v_mul_f32_e32 v115, 0xbfb8aa3b, v128
	v_exp_f32_e32 v115, v115
	s_nop 0
	v_add_f32_e32 v115, 1.0, v115
	v_rcp_f32_e32 v118, v115
	v_mul_f32_e32 v115, 0xbfb8aa3b, v129
	v_exp_f32_e32 v115, v115
	s_nop 0
	v_add_f32_e32 v115, 1.0, v115
	v_rcp_f32_e32 v119, v115
	s_nop 0
	v_pk_mul_f32 v[118:119], v[128:129], v[118:119]
	s_nop 0
	v_pk_mul_f32 v[118:119], v[120:121], v[118:119]
	s_nop 0
	v_cvt_pk_bf16_f32 v115, v118, v119
	v_mul_f32_e32 v118, 0xbfb8aa3b, v122
	v_mul_f32_e32 v119, 0xbfb8aa3b, v123
	v_exp_f32_e32 v118, v118
	v_exp_f32_e32 v119, v119
	s_nop 0
	v_add_f32_e32 v118, 1.0, v118
	v_add_f32_e32 v119, 1.0, v119
	v_rcp_f32_e32 v118, v118
	v_rcp_f32_e32 v119, v119
	s_nop 0
	v_pk_mul_f32 v[118:119], v[122:123], v[118:119]
	s_nop 0
	v_pk_mul_f32 v[116:117], v[116:117], v[118:119]
	s_nop 0
	v_cvt_pk_bf16_f32 v116, v116, v117
	v_mul_f32_e32 v117, 0xbfb8aa3b, v124
	v_exp_f32_e32 v117, v117
	s_nop 0
	v_add_f32_e32 v117, 1.0, v117
	v_rcp_f32_e32 v118, v117
	v_mul_f32_e32 v117, 0xbfb8aa3b, v125
	v_exp_f32_e32 v117, v117
	s_nop 0
	v_add_f32_e32 v117, 1.0, v117
	v_rcp_f32_e32 v119, v117
	s_nop 0
	v_pk_mul_f32 v[118:119], v[124:125], v[118:119]
	s_nop 0
	v_pk_mul_f32 v[118:119], v[136:137], v[118:119]
	s_nop 0
	v_cvt_pk_bf16_f32 v117, v118, v119
	ds_write_b128 v214, v[114:117]
	ds_read_b128 v[220:223], v215
	s_waitcnt lgkmcnt(0)
	global_store_dwordx4 v[134:135], v[220:223], off sc1
	s_nop 1
	v_pk_mul_f32 v[14:15], v[14:15], v[130:131] op_sel_hi:[1,0]
	v_pk_mul_f32 v[116:117], v[100:101], v[176:177] op_sel_hi:[1,0]
	v_pk_mul_f32 v[100:101], v[98:99], v[176:177] op_sel_hi:[1,0]
	v_mul_f32_e32 v98, 0xbfb8aa3b, v110
	v_mul_f32_e32 v99, 0xbfb8aa3b, v111
	v_exp_f32_e32 v98, v98
	v_exp_f32_e32 v99, v99
	v_mad_i64_i32 v[114:115], s[4:5], v168, s6, v[132:133]
	v_add_f32_e32 v98, 1.0, v98
	v_add_f32_e32 v99, 1.0, v99
	v_rcp_f32_e32 v98, v98
	v_rcp_f32_e32 v99, v99
	v_pk_mul_f32 v[6:7], v[6:7], v[130:131] op_sel_hi:[1,0]
	v_pk_mul_f32 v[16:17], v[16:17], v[130:131] op_sel_hi:[1,0]
	v_pk_mul_f32 v[8:9], v[8:9], v[130:131] op_sel_hi:[1,0]
	v_pk_mul_f32 v[98:99], v[110:111], v[98:99]
	v_pk_mul_f32 v[10:11], v[10:11], v[130:131] op_sel_hi:[1,0]
	v_pk_mul_f32 v[98:99], v[102:103], v[98:99]
	v_pk_mul_f32 v[12:13], v[12:13], v[130:131] op_sel_hi:[1,0]
	v_cvt_pk_bf16_f32 v98, v98, v99
	v_mul_f32_e32 v99, 0xbfb8aa3b, v112
	v_exp_f32_e32 v99, v99
	s_andn2_b64 vcc, exec, s[38:39]
	v_add_f32_e32 v99, 1.0, v99
	v_rcp_f32_e32 v102, v99
	v_mul_f32_e32 v99, 0xbfb8aa3b, v113
	v_exp_f32_e32 v99, v99
	s_nop 0
	v_add_f32_e32 v99, 1.0, v99
	v_rcp_f32_e32 v103, v99
	s_nop 0
	v_pk_mul_f32 v[102:103], v[112:113], v[102:103]
	s_nop 0
	v_pk_mul_f32 v[102:103], v[104:105], v[102:103]
	s_nop 0
	v_cvt_pk_bf16_f32 v99, v102, v103
	v_mul_f32_e32 v102, 0xbfb8aa3b, v106
	v_mul_f32_e32 v103, 0xbfb8aa3b, v107
	v_exp_f32_e32 v102, v102
	v_exp_f32_e32 v103, v103
	v_add_f32_e32 v102, 1.0, v102
	v_add_f32_e32 v103, 1.0, v103
	v_rcp_f32_e32 v102, v102
	v_rcp_f32_e32 v103, v103
	s_nop 0
	v_pk_mul_f32 v[102:103], v[106:107], v[102:103]
	s_nop 0
	v_pk_mul_f32 v[100:101], v[100:101], v[102:103]
	s_nop 0
	v_cvt_pk_bf16_f32 v100, v100, v101
	v_mul_f32_e32 v101, 0xbfb8aa3b, v108
	v_exp_f32_e32 v101, v101
	s_nop 0
	v_add_f32_e32 v101, 1.0, v101
	v_rcp_f32_e32 v102, v101
	v_mul_f32_e32 v101, 0xbfb8aa3b, v109
	v_exp_f32_e32 v101, v101
	s_nop 0
	v_add_f32_e32 v101, 1.0, v101
	v_rcp_f32_e32 v103, v101
	s_nop 0
	v_pk_mul_f32 v[102:103], v[108:109], v[102:103]
	s_nop 0
	v_pk_mul_f32 v[102:103], v[116:117], v[102:103]
	s_nop 0
	v_cvt_pk_bf16_f32 v101, v102, v103
	ds_write_b128 v214, v[98:101]
	ds_read_b128 v[224:227], v215
	s_waitcnt lgkmcnt(0)
	global_store_dwordx4 v[114:115], v[224:227], off sc1
	s_nop 1
	v_pk_mul_f32 v[100:101], v[84:85], v[174:175] op_sel_hi:[1,0]
	v_pk_mul_f32 v[84:85], v[82:83], v[174:175] op_sel_hi:[1,0]
	v_mul_f32_e32 v82, 0xbfb8aa3b, v94
	v_mul_f32_e32 v83, 0xbfb8aa3b, v95
	v_exp_f32_e32 v82, v82
	v_exp_f32_e32 v83, v83
	v_mad_i64_i32 v[98:99], s[4:5], v166, s6, v[132:133]
	v_add_f32_e32 v82, 1.0, v82
	v_add_f32_e32 v83, 1.0, v83
	v_rcp_f32_e32 v82, v82
	v_rcp_f32_e32 v83, v83
	s_nop 0
	v_pk_mul_f32 v[82:83], v[94:95], v[82:83]
	s_nop 0
	v_pk_mul_f32 v[82:83], v[86:87], v[82:83]
	s_nop 0
	v_cvt_pk_bf16_f32 v82, v82, v83
	v_mul_f32_e32 v83, 0xbfb8aa3b, v96
	v_exp_f32_e32 v83, v83
	s_nop 0
	v_add_f32_e32 v83, 1.0, v83
	v_rcp_f32_e32 v86, v83
	v_mul_f32_e32 v83, 0xbfb8aa3b, v97
	v_exp_f32_e32 v83, v83
	s_nop 0
	v_add_f32_e32 v83, 1.0, v83
	v_rcp_f32_e32 v87, v83
	s_nop 0
	v_pk_mul_f32 v[86:87], v[96:97], v[86:87]
	s_nop 0
	v_pk_mul_f32 v[86:87], v[88:89], v[86:87]
	s_nop 0
	v_cvt_pk_bf16_f32 v83, v86, v87
	v_mul_f32_e32 v86, 0xbfb8aa3b, v90
	v_mul_f32_e32 v87, 0xbfb8aa3b, v91
	v_exp_f32_e32 v86, v86
	v_exp_f32_e32 v87, v87
	v_add_f32_e32 v86, 1.0, v86
	v_add_f32_e32 v87, 1.0, v87
	v_rcp_f32_e32 v86, v86
	v_rcp_f32_e32 v87, v87
	s_nop 0
	v_pk_mul_f32 v[86:87], v[90:91], v[86:87]
	s_nop 0
	v_pk_mul_f32 v[84:85], v[84:85], v[86:87]
	s_nop 0
	v_cvt_pk_bf16_f32 v84, v84, v85
	v_mul_f32_e32 v85, 0xbfb8aa3b, v92
	v_exp_f32_e32 v85, v85
	s_nop 0
	v_add_f32_e32 v85, 1.0, v85
	v_rcp_f32_e32 v86, v85
	v_mul_f32_e32 v85, 0xbfb8aa3b, v93
	v_exp_f32_e32 v85, v85
	s_nop 0
	v_add_f32_e32 v85, 1.0, v85
	v_rcp_f32_e32 v87, v85
	s_nop 0
	v_pk_mul_f32 v[86:87], v[92:93], v[86:87]
	s_nop 0
	v_pk_mul_f32 v[86:87], v[100:101], v[86:87]
	s_nop 0
	v_cvt_pk_bf16_f32 v85, v86, v87
	ds_write_b128 v214, v[82:85]
	ds_read_b128 v[220:223], v215
	s_waitcnt lgkmcnt(0)
	global_store_dwordx4 v[98:99], v[220:223], off sc1
	s_nop 1
	v_pk_mul_f32 v[84:85], v[68:69], v[178:179] op_sel_hi:[1,0]
	v_pk_mul_f32 v[68:69], v[66:67], v[178:179] op_sel_hi:[1,0]
	v_mul_f32_e32 v66, 0xbfb8aa3b, v78
	v_mul_f32_e32 v67, 0xbfb8aa3b, v79
	v_exp_f32_e32 v66, v66
	v_exp_f32_e32 v67, v67
	v_mad_i64_i32 v[82:83], s[4:5], v170, s6, v[132:133]
	v_add_f32_e32 v66, 1.0, v66
	v_add_f32_e32 v67, 1.0, v67
	v_rcp_f32_e32 v66, v66
	v_rcp_f32_e32 v67, v67
	s_nop 0
	v_pk_mul_f32 v[66:67], v[78:79], v[66:67]
	s_nop 0
	v_pk_mul_f32 v[66:67], v[70:71], v[66:67]
	s_nop 0
	v_cvt_pk_bf16_f32 v66, v66, v67
	v_mul_f32_e32 v67, 0xbfb8aa3b, v80
	v_exp_f32_e32 v67, v67
	s_nop 0
	v_add_f32_e32 v67, 1.0, v67
	v_rcp_f32_e32 v70, v67
	v_mul_f32_e32 v67, 0xbfb8aa3b, v81
	v_exp_f32_e32 v67, v67
	s_nop 0
	v_add_f32_e32 v67, 1.0, v67
	v_rcp_f32_e32 v71, v67
	s_nop 0
	v_pk_mul_f32 v[70:71], v[80:81], v[70:71]
	s_nop 0
	v_pk_mul_f32 v[70:71], v[72:73], v[70:71]
	s_nop 0
	v_cvt_pk_bf16_f32 v67, v70, v71
	v_mul_f32_e32 v70, 0xbfb8aa3b, v74
	v_mul_f32_e32 v71, 0xbfb8aa3b, v75
	v_exp_f32_e32 v70, v70
	v_exp_f32_e32 v71, v71
	v_add_f32_e32 v70, 1.0, v70
	v_add_f32_e32 v71, 1.0, v71
	v_rcp_f32_e32 v70, v70
	v_rcp_f32_e32 v71, v71
	s_nop 0
	v_pk_mul_f32 v[70:71], v[74:75], v[70:71]
	s_nop 0
	v_pk_mul_f32 v[68:69], v[68:69], v[70:71]
	s_nop 0
	v_cvt_pk_bf16_f32 v68, v68, v69
	v_mul_f32_e32 v69, 0xbfb8aa3b, v76
	v_exp_f32_e32 v69, v69
	s_nop 0
	v_add_f32_e32 v69, 1.0, v69
	v_rcp_f32_e32 v70, v69
	v_mul_f32_e32 v69, 0xbfb8aa3b, v77
	v_exp_f32_e32 v69, v69
	s_nop 0
	v_add_f32_e32 v69, 1.0, v69
	v_rcp_f32_e32 v71, v69
	s_nop 0
	v_pk_mul_f32 v[70:71], v[76:77], v[70:71]
	s_nop 0
	v_pk_mul_f32 v[70:71], v[84:85], v[70:71]
	s_nop 0
	v_cvt_pk_bf16_f32 v69, v70, v71
	ds_write_b128 v214, v[66:69]
	ds_read_b128 v[224:227], v215
	s_waitcnt lgkmcnt(0)
	global_store_dwordx4 v[82:83], v[224:227], off sc1
	s_nop 1
	v_pk_mul_f32 v[68:69], v[52:53], v[182:183] op_sel_hi:[1,0]
	v_pk_mul_f32 v[52:53], v[50:51], v[182:183] op_sel_hi:[1,0]
	v_mul_f32_e32 v50, 0xbfb8aa3b, v62
	v_mul_f32_e32 v51, 0xbfb8aa3b, v63
	v_exp_f32_e32 v50, v50
	v_exp_f32_e32 v51, v51
	v_mad_i64_i32 v[66:67], s[4:5], v172, s6, v[132:133]
	v_add_f32_e32 v50, 1.0, v50
	v_add_f32_e32 v51, 1.0, v51
	v_rcp_f32_e32 v50, v50
	v_rcp_f32_e32 v51, v51
	s_nop 0
	v_pk_mul_f32 v[50:51], v[62:63], v[50:51]
	s_nop 0
	v_pk_mul_f32 v[50:51], v[54:55], v[50:51]
	s_nop 0
	v_cvt_pk_bf16_f32 v50, v50, v51
	v_mul_f32_e32 v51, 0xbfb8aa3b, v64
	v_exp_f32_e32 v51, v51
	s_nop 0
	v_add_f32_e32 v51, 1.0, v51
	v_rcp_f32_e32 v54, v51
	v_mul_f32_e32 v51, 0xbfb8aa3b, v65
	v_exp_f32_e32 v51, v51
	s_nop 0
	v_add_f32_e32 v51, 1.0, v51
	v_rcp_f32_e32 v55, v51
	s_nop 0
	v_pk_mul_f32 v[54:55], v[64:65], v[54:55]
	s_nop 0
	v_pk_mul_f32 v[54:55], v[56:57], v[54:55]
	s_nop 0
	v_cvt_pk_bf16_f32 v51, v54, v55
	v_mul_f32_e32 v54, 0xbfb8aa3b, v58
	v_mul_f32_e32 v55, 0xbfb8aa3b, v59
	v_exp_f32_e32 v54, v54
	v_exp_f32_e32 v55, v55
	v_add_f32_e32 v54, 1.0, v54
	v_add_f32_e32 v55, 1.0, v55
	v_rcp_f32_e32 v54, v54
	v_rcp_f32_e32 v55, v55
	s_nop 0
	v_pk_mul_f32 v[54:55], v[58:59], v[54:55]
	s_nop 0
	v_pk_mul_f32 v[52:53], v[52:53], v[54:55]
	s_nop 0
	v_cvt_pk_bf16_f32 v52, v52, v53
	v_mul_f32_e32 v53, 0xbfb8aa3b, v60
	v_exp_f32_e32 v53, v53
	s_nop 0
	v_add_f32_e32 v53, 1.0, v53
	v_rcp_f32_e32 v54, v53
	v_mul_f32_e32 v53, 0xbfb8aa3b, v61
	v_exp_f32_e32 v53, v53
	s_nop 0
	v_add_f32_e32 v53, 1.0, v53
	v_rcp_f32_e32 v55, v53
	s_nop 0
	v_pk_mul_f32 v[54:55], v[60:61], v[54:55]
	s_nop 0
	v_pk_mul_f32 v[54:55], v[68:69], v[54:55]
	s_nop 0
	v_cvt_pk_bf16_f32 v53, v54, v55
	ds_write_b128 v214, v[50:53]
	ds_read_b128 v[220:223], v215
	s_waitcnt lgkmcnt(0)
	global_store_dwordx4 v[66:67], v[220:223], off sc1
	s_nop 1
	v_pk_mul_f32 v[52:53], v[36:37], v[186:187] op_sel_hi:[1,0]
	v_pk_mul_f32 v[36:37], v[34:35], v[186:187] op_sel_hi:[1,0]
	v_mul_f32_e32 v34, 0xbfb8aa3b, v46
	v_mul_f32_e32 v35, 0xbfb8aa3b, v47
	v_exp_f32_e32 v34, v34
	v_exp_f32_e32 v35, v35
	v_mad_i64_i32 v[50:51], s[4:5], v184, s6, v[132:133]
	v_add_f32_e32 v34, 1.0, v34
	v_add_f32_e32 v35, 1.0, v35
	v_rcp_f32_e32 v34, v34
	v_rcp_f32_e32 v35, v35
	s_nop 0
	v_pk_mul_f32 v[34:35], v[46:47], v[34:35]
	s_nop 0
	v_pk_mul_f32 v[34:35], v[38:39], v[34:35]
	s_nop 0
	v_cvt_pk_bf16_f32 v34, v34, v35
	v_mul_f32_e32 v35, 0xbfb8aa3b, v48
	v_exp_f32_e32 v35, v35
	s_nop 0
	v_add_f32_e32 v35, 1.0, v35
	v_rcp_f32_e32 v38, v35
	v_mul_f32_e32 v35, 0xbfb8aa3b, v49
	v_exp_f32_e32 v35, v35
	s_nop 0
	v_add_f32_e32 v35, 1.0, v35
	v_rcp_f32_e32 v39, v35
	s_nop 0
	v_pk_mul_f32 v[38:39], v[48:49], v[38:39]
	s_nop 0
	v_pk_mul_f32 v[38:39], v[40:41], v[38:39]
	s_nop 0
	v_cvt_pk_bf16_f32 v35, v38, v39
	v_mul_f32_e32 v38, 0xbfb8aa3b, v42
	v_mul_f32_e32 v39, 0xbfb8aa3b, v43
	v_exp_f32_e32 v38, v38
	v_exp_f32_e32 v39, v39
	v_add_f32_e32 v38, 1.0, v38
	v_add_f32_e32 v39, 1.0, v39
	v_rcp_f32_e32 v38, v38
	v_rcp_f32_e32 v39, v39
	s_nop 0
	v_pk_mul_f32 v[38:39], v[42:43], v[38:39]
	s_nop 0
	v_pk_mul_f32 v[36:37], v[36:37], v[38:39]
	s_nop 0
	v_cvt_pk_bf16_f32 v36, v36, v37
	v_mul_f32_e32 v37, 0xbfb8aa3b, v44
	v_exp_f32_e32 v37, v37
	s_nop 0
	v_add_f32_e32 v37, 1.0, v37
	v_rcp_f32_e32 v38, v37
	v_mul_f32_e32 v37, 0xbfb8aa3b, v45
	v_exp_f32_e32 v37, v37
	s_nop 0
	v_add_f32_e32 v37, 1.0, v37
	v_rcp_f32_e32 v39, v37
	s_nop 0
	v_pk_mul_f32 v[38:39], v[44:45], v[38:39]
	s_nop 0
	v_pk_mul_f32 v[38:39], v[52:53], v[38:39]
	s_nop 0
	v_cvt_pk_bf16_f32 v37, v38, v39
	ds_write_b128 v214, v[34:37]
	ds_read_b128 v[224:227], v215
	s_waitcnt lgkmcnt(0)
	global_store_dwordx4 v[50:51], v[224:227], off sc1
	s_nop 1
	v_pk_mul_f32 v[36:37], v[20:21], v[190:191] op_sel_hi:[1,0]
	v_pk_mul_f32 v[20:21], v[18:19], v[190:191] op_sel_hi:[1,0]
	v_mul_f32_e32 v18, 0xbfb8aa3b, v30
	v_mul_f32_e32 v19, 0xbfb8aa3b, v31
	v_exp_f32_e32 v18, v18
	v_exp_f32_e32 v19, v19
	v_mad_i64_i32 v[34:35], s[4:5], v188, s6, v[132:133]
	v_add_f32_e32 v18, 1.0, v18
	v_add_f32_e32 v19, 1.0, v19
	v_rcp_f32_e32 v18, v18
	v_rcp_f32_e32 v19, v19
	s_nop 0
	v_pk_mul_f32 v[18:19], v[30:31], v[18:19]
	s_nop 0
	v_pk_mul_f32 v[18:19], v[22:23], v[18:19]
	s_nop 0
	v_cvt_pk_bf16_f32 v18, v18, v19
	v_mul_f32_e32 v19, 0xbfb8aa3b, v32
	v_exp_f32_e32 v19, v19
	s_nop 0
	v_add_f32_e32 v19, 1.0, v19
	v_rcp_f32_e32 v22, v19
	v_mul_f32_e32 v19, 0xbfb8aa3b, v33
	v_exp_f32_e32 v19, v19
	s_nop 0
	v_add_f32_e32 v19, 1.0, v19
	v_rcp_f32_e32 v23, v19
	s_nop 0
	v_pk_mul_f32 v[22:23], v[32:33], v[22:23]
	s_nop 0
	v_pk_mul_f32 v[22:23], v[24:25], v[22:23]
	s_nop 0
	v_cvt_pk_bf16_f32 v19, v22, v23
	v_mul_f32_e32 v22, 0xbfb8aa3b, v26
	v_mul_f32_e32 v23, 0xbfb8aa3b, v27
	v_exp_f32_e32 v22, v22
	v_exp_f32_e32 v23, v23
	v_add_f32_e32 v22, 1.0, v22
	v_add_f32_e32 v23, 1.0, v23
	v_rcp_f32_e32 v22, v22
	v_rcp_f32_e32 v23, v23
	s_nop 0
	v_pk_mul_f32 v[22:23], v[26:27], v[22:23]
	s_nop 0
	v_pk_mul_f32 v[20:21], v[20:21], v[22:23]
	s_nop 0
	v_cvt_pk_bf16_f32 v20, v20, v21
	v_mul_f32_e32 v21, 0xbfb8aa3b, v28
	v_exp_f32_e32 v21, v21
	s_nop 0
	v_add_f32_e32 v21, 1.0, v21
	v_rcp_f32_e32 v22, v21
	v_mul_f32_e32 v21, 0xbfb8aa3b, v29
	v_exp_f32_e32 v21, v21
	s_nop 0
	v_add_f32_e32 v21, 1.0, v21
	v_rcp_f32_e32 v23, v21
	s_nop 0
	v_pk_mul_f32 v[22:23], v[28:29], v[22:23]
	s_nop 0
	v_pk_mul_f32 v[22:23], v[36:37], v[22:23]
	s_nop 0
	v_cvt_pk_bf16_f32 v21, v22, v23
	ds_write_b128 v214, v[18:21]
	ds_read_b128 v[220:223], v215
	s_waitcnt lgkmcnt(0)
	global_store_dwordx4 v[34:35], v[220:223], off sc1
	s_nop 1
	v_pk_mul_f32 v[20:21], v[4:5], v[130:131] op_sel_hi:[1,0]
	v_pk_mul_f32 v[4:5], v[2:3], v[130:131] op_sel_hi:[1,0]
	v_mul_f32_e32 v2, 0xbfb8aa3b, v14
	v_mul_f32_e32 v3, 0xbfb8aa3b, v15
	v_exp_f32_e32 v2, v2
	v_exp_f32_e32 v3, v3
	v_mad_i64_i32 v[18:19], s[4:5], v192, s6, v[132:133]
	v_add_f32_e32 v2, 1.0, v2
	v_add_f32_e32 v3, 1.0, v3
	v_rcp_f32_e32 v2, v2
	v_rcp_f32_e32 v3, v3
	s_mov_b64 s[6:7], -1
	v_pk_mul_f32 v[2:3], v[14:15], v[2:3]
	s_nop 0
	v_pk_mul_f32 v[2:3], v[6:7], v[2:3]
	s_nop 0
	v_cvt_pk_bf16_f32 v2, v2, v3
	v_mul_f32_e32 v3, 0xbfb8aa3b, v16
	v_exp_f32_e32 v3, v3
	s_nop 0
	v_add_f32_e32 v3, 1.0, v3
	v_rcp_f32_e32 v6, v3
	v_mul_f32_e32 v3, 0xbfb8aa3b, v17
	v_exp_f32_e32 v3, v3
	s_nop 0
	v_add_f32_e32 v3, 1.0, v3
	v_rcp_f32_e32 v7, v3
	s_nop 0
	v_pk_mul_f32 v[6:7], v[16:17], v[6:7]
	s_nop 0
	v_pk_mul_f32 v[6:7], v[8:9], v[6:7]
	s_nop 0
	v_cvt_pk_bf16_f32 v3, v6, v7
	v_mul_f32_e32 v6, 0xbfb8aa3b, v10
	v_mul_f32_e32 v7, 0xbfb8aa3b, v11
	v_exp_f32_e32 v6, v6
	v_exp_f32_e32 v7, v7
	v_add_f32_e32 v6, 1.0, v6
	v_add_f32_e32 v7, 1.0, v7
	v_rcp_f32_e32 v6, v6
	v_rcp_f32_e32 v7, v7
	s_nop 0
	v_pk_mul_f32 v[6:7], v[10:11], v[6:7]
	s_nop 0
	v_pk_mul_f32 v[4:5], v[4:5], v[6:7]
	s_nop 0
	v_cvt_pk_bf16_f32 v4, v4, v5
	v_mul_f32_e32 v5, 0xbfb8aa3b, v12
	v_exp_f32_e32 v5, v5
	s_nop 0
	v_add_f32_e32 v5, 1.0, v5
	v_rcp_f32_e32 v6, v5
	v_mul_f32_e32 v5, 0xbfb8aa3b, v13
	v_exp_f32_e32 v5, v5
	s_nop 0
	v_add_f32_e32 v5, 1.0, v5
	v_rcp_f32_e32 v7, v5
	s_nop 0
	v_pk_mul_f32 v[6:7], v[12:13], v[6:7]
	s_nop 0
	v_pk_mul_f32 v[6:7], v[20:21], v[6:7]
	s_nop 0
	v_cvt_pk_bf16_f32 v5, v6, v7
	ds_write_b128 v214, v[2:5]
	ds_read_b128 v[224:227], v215
	s_waitcnt lgkmcnt(0)
	global_store_dwordx4 v[18:19], v[224:227], off sc1
	s_cbranch_vccnz .LBB0_600
	s_andn2_b64 vcc, exec, s[10:11]
	s_cbranch_vccnz .LBB0_599
	s_barrier
	s_branch .LBB0_599
